# FFI K-loop: MFMA phase pairs merged (32 MFMAs per barrier pair, 8 barriers per iteration instead of 16), B1 reads hoisted, stages regrouped, vmcnt(8)
# speedup vs baseline: 1.0021x; 1.0021x over previous
; #define G_STAGE(bufoff, gbase, o0, h64) do { \
;         __builtin_amdgcn_global_load_lds((const unsigned*)((const char*)(gbase) + (o0)), (LAS unsigned*)(lds + (bufoff) + ldsw), 16, 0, 0); \
;         __builtin_amdgcn_global_load_lds((const unsigned*)((const char*)(gbase) + (h64) + (o0)), (LAS unsigned*)(lds + (bufoff) + ldsw + 8192), 16, 0, 0); } while (0)
; #define G_LDA(dst, b, h) do { _Pragma("unroll") for (int m = 0; m < 4; ++m) _Pragma("unroll") for (int k = 0; k < 2; ++k) dst[m][k] = *(const LAS bf16x8*)(lds + G_SA(b, h) + aoff + m * 2048 + k * 1024); } while (0)
; #define G_LDB(dst, b, h) do { _Pragma("unroll") for (int n = 0; n < 2; ++n) _Pragma("unroll") for (int k = 0; k < 2; ++k) dst[n][k] = *(const LAS bf16x8*)(lds + G_SB(b, h) + boff + n * 2048 + k * 1024); } while (0)
; #define G_WAIT_V(n) asm volatile("s_waitcnt vmcnt(" #n ")" ::: "memory")
; #define G_WAIT_L(n) asm volatile("s_waitcnt lgkmcnt(" #n ")" ::: "memory")
; #define G_BAR __builtin_amdgcn_s_barrier()
; #define G_SCHED __builtin_amdgcn_sched_barrier(0)
;     ...
;         for (int t = 0; t < nt; t += 2) {
;             const bool last = (t == nt - 2);
;             const char* a1 = cA + (size_t)(t + 1) * ckA;
;             const char* a2 = last ? nA : cA + (size_t)(t + 2) * ckA; const char* b2 = last ? nB : cB + (size_t)(t + 2) * kB;
;             const char* a3 = a2 + ckA; const char* b3 = b2 + kB;
;             G_LDB(B0, 0, 0); G_SCHED; G_LDA(At, 0, 0); G_STAGE(G_SA(1, 1), a1 + chA, cA0, qA);
;             G_WAIT_L(8); G_BAR; G_WAIT_L(0); G_MMA(0, 0, At, B0); G_BAR; G_SCHED;
;             G_LDB(B1, 0, 1); G_STAGE(G_SB(0, 0), b2, cB0, qB);
;             G_BAR; G_WAIT_L(0); G_MMA(0, 1, At, B1); G_BAR;
;             G_LDA(At, 0, 1); G_STAGE(G_SA(0, 0), a2, cA0, qA);
;             G_BAR; G_WAIT_L(0); G_MMA(1, 0, At, B0); G_BAR; G_SCHED;
;             G_STAGE(G_SB(0, 1), b2 + chB, cB0, qB);
;             G_WAIT_V(6); G_BAR; G_MMA(1, 1, At, B1); G_BAR;
.LBB0_1120:
	s_add_u32 s4, s2, 0xfffc0080
	s_addc_u32 s5, s3, -1
	s_add_i32 s19, 0, 0x10000
	v_add_u32_e32 v0, s19, v149
	ds_read_b128 v[140:143], v0
	ds_read_b128 v[144:147], v0 offset:1024
	ds_read_b128 v[152:155], v0 offset:2048
	ds_read_b128 v[156:159], v0 offset:3072
	s_cmp_eq_u32 s18, 12
	s_cselect_b32 s5, s13, s5
	s_cselect_b32 s4, s12, s4
	s_cselect_b32 s41, s15, s17
	s_cselect_b32 s40, s14, s16
	v_lshl_add_u64 v[184:185], s[2:3], 0, v[138:139]
	s_add_i32 m0, s26, 0xc000
	ds_read_b128 v[160:163], v150
	ds_read_b128 v[164:167], v150 offset:1024
	ds_read_b128 v[172:175], v150 offset:2048
	ds_read_b128 v[176:179], v150 offset:3072
	ds_read_b128 v[180:183], v150 offset:4096
	ds_read_b128 v[196:199], v150 offset:5120
	ds_read_b128 v[200:203], v150 offset:6144
	ds_read_b128 v[204:207], v150 offset:7168
	global_load_lds_dwordx4 v[184:185], off
	v_lshl_add_u64 v[184:185], v[184:185], 0, s[0:1]
	s_add_i32 m0, s26, 0xe000
	s_nop 0
	global_load_lds_dwordx4 v[184:185], off
	s_add_i32 s39, 0, 0x14000
	v_add_u32_e32 v0, s39, v149
	ds_read_b128 v[208:211], v0
	ds_read_b128 v[212:215], v0 offset:1024
	ds_read_b128 v[216:219], v0 offset:2048
	ds_read_b128 v[220:223], v0 offset:3072
	s_waitcnt vmcnt(8)
	s_waitcnt lgkmcnt(0)
	s_barrier
	s_setprio 3
	v_mfma_f32_16x16x32_bf16 v[132:135], v[140:143], v[160:163], v[132:135]
	v_mfma_f32_16x16x32_bf16 v[124:127], v[152:155], v[160:163], v[124:127]
	v_mfma_f32_16x16x32_bf16 v[116:119], v[140:143], v[172:175], v[116:119]
	v_mfma_f32_16x16x32_bf16 v[108:111], v[152:155], v[172:175], v[108:111]
	v_mfma_f32_16x16x32_bf16 v[100:103], v[140:143], v[180:183], v[100:103]
	v_mfma_f32_16x16x32_bf16 v[92:95], v[152:155], v[180:183], v[92:95]
	v_mfma_f32_16x16x32_bf16 v[84:87], v[140:143], v[200:203], v[84:87]
	v_mfma_f32_16x16x32_bf16 v[76:79], v[152:155], v[200:203], v[76:79]
	v_mfma_f32_16x16x32_bf16 v[132:135], v[144:147], v[164:167], v[132:135]
	v_mfma_f32_16x16x32_bf16 v[124:127], v[156:159], v[164:167], v[124:127]
	v_mfma_f32_16x16x32_bf16 v[116:119], v[144:147], v[176:179], v[116:119]
	v_mfma_f32_16x16x32_bf16 v[108:111], v[156:159], v[176:179], v[108:111]
	v_mfma_f32_16x16x32_bf16 v[100:103], v[144:147], v[196:199], v[100:103]
	v_mfma_f32_16x16x32_bf16 v[92:95], v[156:159], v[196:199], v[92:95]
	v_mfma_f32_16x16x32_bf16 v[84:87], v[144:147], v[204:207], v[84:87]
	v_mfma_f32_16x16x32_bf16 v[76:79], v[156:159], v[204:207], v[76:79]
	v_mfma_f32_16x16x32_bf16 v[128:131], v[208:211], v[160:163], v[128:131]
	v_mfma_f32_16x16x32_bf16 v[120:123], v[216:219], v[160:163], v[120:123]
	v_mfma_f32_16x16x32_bf16 v[112:115], v[208:211], v[172:175], v[112:115]
	v_mfma_f32_16x16x32_bf16 v[104:107], v[216:219], v[172:175], v[104:107]
	v_mfma_f32_16x16x32_bf16 v[96:99], v[208:211], v[180:183], v[96:99]
	v_mfma_f32_16x16x32_bf16 v[88:91], v[216:219], v[180:183], v[88:91]
	v_mfma_f32_16x16x32_bf16 v[80:83], v[208:211], v[200:203], v[80:83]
	v_mfma_f32_16x16x32_bf16 v[72:75], v[216:219], v[200:203], v[72:75]
	v_mfma_f32_16x16x32_bf16 v[128:131], v[212:215], v[164:167], v[128:131]
	v_mfma_f32_16x16x32_bf16 v[120:123], v[220:223], v[164:167], v[120:123]
	v_mfma_f32_16x16x32_bf16 v[112:115], v[212:215], v[176:179], v[112:115]
	v_mfma_f32_16x16x32_bf16 v[104:107], v[220:223], v[176:179], v[104:107]
	v_mfma_f32_16x16x32_bf16 v[96:99], v[212:215], v[196:199], v[96:99]
	v_mfma_f32_16x16x32_bf16 v[88:91], v[220:223], v[196:199], v[88:91]
	v_mfma_f32_16x16x32_bf16 v[80:83], v[212:215], v[204:207], v[80:83]
	v_mfma_f32_16x16x32_bf16 v[72:75], v[220:223], v[204:207], v[72:75]
	s_setprio 0
	s_mov_b32 m0, s26
	v_lshl_add_u64 v[224:225], s[4:5], 0, v[136:137]
	s_barrier
	ds_read_b128 v[160:163], v150 offset:16384
	ds_read_b128 v[164:167], v150 offset:17408
	ds_read_b128 v[172:175], v150 offset:18432
	ds_read_b128 v[176:179], v150 offset:19456
	ds_read_b128 v[180:183], v150 offset:20480
	ds_read_b128 v[196:199], v150 offset:21504
	ds_read_b128 v[200:203], v150 offset:22528
	ds_read_b128 v[204:207], v150 offset:23552
	global_load_lds_dwordx4 v[224:225], off
	v_lshl_add_u64 v[226:227], v[224:225], 0, s[0:1]
	s_mov_b32 m0, s27
	s_nop 0
	global_load_lds_dwordx4 v[226:227], off
	s_add_i32 s19, s19, s21
	v_lshl_add_u64 v[184:185], s[40:41], 0, v[2:3]
	s_mov_b32 m0, s19
	s_nop 0
	global_load_lds_dwordx4 v[184:185], off
	v_lshl_add_u64 v[234:235], v[184:185], 0, s[0:1]
	s_add_i32 m0, s19, 0x2000
	s_nop 0
	global_load_lds_dwordx4 v[234:235], off
	s_add_i32 s4, s39, s21
	v_lshl_add_u64 v[236:237], v[184:185], 0, s[42:43]
	s_mov_b32 m0, s4
	s_nop 0
	global_load_lds_dwordx4 v[236:237], off
	v_lshl_add_u64 v[236:237], v[184:185], 0, s[50:51]
	s_add_i32 m0, s4, 0x2000
	s_nop 0
	global_load_lds_dwordx4 v[236:237], off
	s_waitcnt vmcnt(8)
	s_waitcnt lgkmcnt(0)
	s_barrier
; #define G_STAGE(bufoff, gbase, o0, h64) do { \
;         __builtin_amdgcn_global_load_lds((const unsigned*)((const char*)(gbase) + (o0)), (LAS unsigned*)(lds + (bufoff) + ldsw), 16, 0, 0); \
;         __builtin_amdgcn_global_load_lds((const unsigned*)((const char*)(gbase) + (h64) + (o0)), (LAS unsigned*)(lds + (bufoff) + ldsw + 8192), 16, 0, 0); } while (0)
; #define G_LDA(dst, b, h) do { _Pragma("unroll") for (int m = 0; m < 4; ++m) _Pragma("unroll") for (int k = 0; k < 2; ++k) dst[m][k] = *(const LAS bf16x8*)(lds + G_SA(b, h) + aoff + m * 2048 + k * 1024); } while (0)
; #define G_LDB(dst, b, h) do { _Pragma("unroll") for (int n = 0; n < 2; ++n) _Pragma("unroll") for (int k = 0; k < 2; ++k) dst[n][k] = *(const LAS bf16x8*)(lds + G_SB(b, h) + boff + n * 2048 + k * 1024); } while (0)
; #define G_WAIT_V(n) asm volatile("s_waitcnt vmcnt(" #n ")" ::: "memory")
; #define G_WAIT_L(n) asm volatile("s_waitcnt lgkmcnt(" #n ")" ::: "memory")
; #define G_BAR __builtin_amdgcn_s_barrier()
; #define G_SCHED __builtin_amdgcn_sched_barrier(0)
;     ...
;             G_WAIT_V(6); G_BAR; G_MMA(1, 1, At, B1); G_BAR;
;             G_LDB(B0, 1, 0); G_SCHED; G_LDA(At, 1, 0); G_STAGE(G_SA(0, 1), a2 + chA, cA0, qA);
;             G_WAIT_L(8); G_BAR; G_WAIT_L(0); G_MMA(0, 0, At, B0); G_BAR; G_SCHED;
	s_setprio 3
	v_mfma_f32_16x16x32_bf16 v[68:71], v[140:143], v[160:163], v[68:71]
	v_mfma_f32_16x16x32_bf16 v[60:63], v[152:155], v[160:163], v[60:63]
	v_mfma_f32_16x16x32_bf16 v[52:55], v[140:143], v[172:175], v[52:55]
	v_mfma_f32_16x16x32_bf16 v[44:47], v[152:155], v[172:175], v[44:47]
	v_mfma_f32_16x16x32_bf16 v[36:39], v[140:143], v[180:183], v[36:39]
	v_mfma_f32_16x16x32_bf16 v[28:31], v[152:155], v[180:183], v[28:31]
	v_mfma_f32_16x16x32_bf16 v[20:23], v[140:143], v[200:203], v[20:23]
	v_mfma_f32_16x16x32_bf16 v[12:15], v[152:155], v[200:203], v[12:15]
	v_mfma_f32_16x16x32_bf16 v[68:71], v[144:147], v[164:167], v[68:71]
	v_mfma_f32_16x16x32_bf16 v[60:63], v[156:159], v[164:167], v[60:63]
	v_mfma_f32_16x16x32_bf16 v[52:55], v[144:147], v[176:179], v[52:55]
	v_mfma_f32_16x16x32_bf16 v[44:47], v[156:159], v[176:179], v[44:47]
	v_mfma_f32_16x16x32_bf16 v[36:39], v[144:147], v[196:199], v[36:39]
	v_mfma_f32_16x16x32_bf16 v[28:31], v[156:159], v[196:199], v[28:31]
	v_mfma_f32_16x16x32_bf16 v[20:23], v[144:147], v[204:207], v[20:23]
	v_mfma_f32_16x16x32_bf16 v[12:15], v[156:159], v[204:207], v[12:15]
	v_mfma_f32_16x16x32_bf16 v[64:67], v[208:211], v[160:163], v[64:67]
	v_mfma_f32_16x16x32_bf16 v[56:59], v[216:219], v[160:163], v[56:59]
	v_mfma_f32_16x16x32_bf16 v[48:51], v[208:211], v[172:175], v[48:51]
	v_mfma_f32_16x16x32_bf16 v[40:43], v[216:219], v[172:175], v[40:43]
	v_mfma_f32_16x16x32_bf16 v[32:35], v[208:211], v[180:183], v[32:35]
	v_mfma_f32_16x16x32_bf16 v[24:27], v[216:219], v[180:183], v[24:27]
	v_mfma_f32_16x16x32_bf16 v[16:19], v[208:211], v[200:203], v[16:19]
	v_mfma_f32_16x16x32_bf16 v[8:11], v[216:219], v[200:203], v[8:11]
	v_mfma_f32_16x16x32_bf16 v[64:67], v[212:215], v[164:167], v[64:67]
	v_mfma_f32_16x16x32_bf16 v[56:59], v[220:223], v[164:167], v[56:59]
	v_mfma_f32_16x16x32_bf16 v[48:51], v[212:215], v[176:179], v[48:51]
	v_mfma_f32_16x16x32_bf16 v[40:43], v[220:223], v[176:179], v[40:43]
	v_mfma_f32_16x16x32_bf16 v[32:35], v[212:215], v[196:199], v[32:35]
	v_mfma_f32_16x16x32_bf16 v[24:27], v[220:223], v[196:199], v[24:27]
	v_mfma_f32_16x16x32_bf16 v[16:19], v[212:215], v[204:207], v[16:19]
	v_mfma_f32_16x16x32_bf16 v[8:11], v[220:223], v[204:207], v[8:11]
	s_setprio 0
	s_add_i32 s4, 0, 0x18000
	v_add_u32_e32 v0, s4, v149
	s_barrier
	ds_read_b128 v[140:143], v0
	ds_read_b128 v[144:147], v0 offset:1024
	ds_read_b128 v[152:155], v0 offset:2048
	ds_read_b128 v[156:159], v0 offset:3072
	s_mov_b32 m0, s29
	v_lshl_add_u64 v[242:243], v[224:225], 0, s[42:43]
	ds_read_b128 v[160:163], v150 offset:32768
	ds_read_b128 v[164:167], v150 offset:33792
	ds_read_b128 v[172:175], v150 offset:34816
	ds_read_b128 v[176:179], v150 offset:35840
	ds_read_b128 v[180:183], v150 offset:36864
	ds_read_b128 v[196:199], v150 offset:37888
	ds_read_b128 v[200:203], v150 offset:38912
	ds_read_b128 v[204:207], v150 offset:39936
	global_load_lds_dwordx4 v[242:243], off
	v_lshl_add_u64 v[242:243], v[224:225], 0, s[50:51]
	s_mov_b32 m0, s30
	s_nop 0
	global_load_lds_dwordx4 v[242:243], off
	s_add_i32 s5, 0, 0x1c000
	v_add_u32_e32 v0, s5, v149
	ds_read_b128 v[208:211], v0
	ds_read_b128 v[212:215], v0 offset:1024
	ds_read_b128 v[216:219], v0 offset:2048
	ds_read_b128 v[220:223], v0 offset:3072
	s_waitcnt vmcnt(8)
	s_waitcnt lgkmcnt(0)
	s_barrier
	s_setprio 3
	v_mfma_f32_16x16x32_bf16 v[132:135], v[140:143], v[160:163], v[132:135]
	v_mfma_f32_16x16x32_bf16 v[124:127], v[152:155], v[160:163], v[124:127]
	v_mfma_f32_16x16x32_bf16 v[116:119], v[140:143], v[172:175], v[116:119]
	v_mfma_f32_16x16x32_bf16 v[108:111], v[152:155], v[172:175], v[108:111]
	v_mfma_f32_16x16x32_bf16 v[100:103], v[140:143], v[180:183], v[100:103]
	v_mfma_f32_16x16x32_bf16 v[92:95], v[152:155], v[180:183], v[92:95]
	v_mfma_f32_16x16x32_bf16 v[84:87], v[140:143], v[200:203], v[84:87]
	v_mfma_f32_16x16x32_bf16 v[76:79], v[152:155], v[200:203], v[76:79]
	v_mfma_f32_16x16x32_bf16 v[132:135], v[144:147], v[164:167], v[132:135]
	v_mfma_f32_16x16x32_bf16 v[124:127], v[156:159], v[164:167], v[124:127]
	v_mfma_f32_16x16x32_bf16 v[116:119], v[144:147], v[176:179], v[116:119]
	v_mfma_f32_16x16x32_bf16 v[108:111], v[156:159], v[176:179], v[108:111]
	v_mfma_f32_16x16x32_bf16 v[100:103], v[144:147], v[196:199], v[100:103]
	v_mfma_f32_16x16x32_bf16 v[92:95], v[156:159], v[196:199], v[92:95]
	v_mfma_f32_16x16x32_bf16 v[84:87], v[144:147], v[204:207], v[84:87]
	v_mfma_f32_16x16x32_bf16 v[76:79], v[156:159], v[204:207], v[76:79]
	v_mfma_f32_16x16x32_bf16 v[128:131], v[208:211], v[160:163], v[128:131]
	v_mfma_f32_16x16x32_bf16 v[120:123], v[216:219], v[160:163], v[120:123]
	v_mfma_f32_16x16x32_bf16 v[112:115], v[208:211], v[172:175], v[112:115]
	v_mfma_f32_16x16x32_bf16 v[104:107], v[216:219], v[172:175], v[104:107]
	v_mfma_f32_16x16x32_bf16 v[96:99], v[208:211], v[180:183], v[96:99]
	v_mfma_f32_16x16x32_bf16 v[88:91], v[216:219], v[180:183], v[88:91]
	v_mfma_f32_16x16x32_bf16 v[80:83], v[208:211], v[200:203], v[80:83]
	v_mfma_f32_16x16x32_bf16 v[72:75], v[216:219], v[200:203], v[72:75]
	v_mfma_f32_16x16x32_bf16 v[128:131], v[212:215], v[164:167], v[128:131]
	v_mfma_f32_16x16x32_bf16 v[120:123], v[220:223], v[164:167], v[120:123]
	v_mfma_f32_16x16x32_bf16 v[112:115], v[212:215], v[176:179], v[112:115]
	v_mfma_f32_16x16x32_bf16 v[104:107], v[220:223], v[176:179], v[104:107]
	v_mfma_f32_16x16x32_bf16 v[96:99], v[212:215], v[196:199], v[96:99]
	v_mfma_f32_16x16x32_bf16 v[88:91], v[220:223], v[196:199], v[88:91]
	v_mfma_f32_16x16x32_bf16 v[80:83], v[212:215], v[204:207], v[80:83]
	v_mfma_f32_16x16x32_bf16 v[72:75], v[220:223], v[204:207], v[72:75]
	s_setprio 0
	s_mov_b32 m0, s31
	v_lshl_add_u64 v[226:227], v[224:225], 0, s[46:47]
	s_barrier
; #define G_STAGE(bufoff, gbase, o0, h64) do { \
;         __builtin_amdgcn_global_load_lds((const unsigned*)((const char*)(gbase) + (o0)), (LAS unsigned*)(lds + (bufoff) + ldsw), 16, 0, 0); \
;         __builtin_amdgcn_global_load_lds((const unsigned*)((const char*)(gbase) + (h64) + (o0)), (LAS unsigned*)(lds + (bufoff) + ldsw + 8192), 16, 0, 0); } while (0)
; #define G_LDA(dst, b, h) do { _Pragma("unroll") for (int m = 0; m < 4; ++m) _Pragma("unroll") for (int k = 0; k < 2; ++k) dst[m][k] = *(const LAS bf16x8*)(lds + G_SA(b, h) + aoff + m * 2048 + k * 1024); } while (0)
; #define G_LDB(dst, b, h) do { _Pragma("unroll") for (int n = 0; n < 2; ++n) _Pragma("unroll") for (int k = 0; k < 2; ++k) dst[n][k] = *(const LAS bf16x8*)(lds + G_SB(b, h) + boff + n * 2048 + k * 1024); } while (0)
; #define G_WAIT_V(n) asm volatile("s_waitcnt vmcnt(" #n ")" ::: "memory")
; #define G_WAIT_L(n) asm volatile("s_waitcnt lgkmcnt(" #n ")" ::: "memory")
; #define G_BAR __builtin_amdgcn_s_barrier()
; #define G_SCHED __builtin_amdgcn_sched_barrier(0)
;     template <int KIND> __device__ __forceinline__ void run(f32x4 (&acc)[2][2][4][2], const Unit& u, int tid_in) const {
;     ...
;         if constexpr (KIND == K_FFI) { bf16_t* act = zb; float rs[8]; get_rs(u, wr, fr, rs);
; #pragma unroll
;             for (int ai = 0; ai < 2; ++ai)
; #pragma unroll
;                 for (int m = 0; m < 4; ++m) { int row = rbase + ai * 128 + m * 16; asm volatile("" : "+v"(row)); const float r = rs[ai * 4 + m]; f32x4 o[2];
;     ...
;             G_LDB(B1, 1, 1); G_STAGE(G_SB(1, 0), b3, cB0, qB);
;             G_BAR; G_WAIT_L(0); G_MMA(0, 1, At, B1); G_BAR;
;             G_LDA(At, 1, 1); G_STAGE(G_SA(1, 0), a3, cA0, qA);
;             G_BAR; G_WAIT_L(0); G_MMA(1, 0, At, B0); G_BAR; G_SCHED;
;             G_STAGE(G_SB(1, 1), b3 + chB, cB0, qB);
;             G_WAIT_V(6); G_BAR; G_MMA(1, 1, At, B1); G_BAR;
;         }
	ds_read_b128 v[160:163], v150 offset:49152
	ds_read_b128 v[164:167], v150 offset:50176
	ds_read_b128 v[172:175], v150 offset:51200
	ds_read_b128 v[176:179], v150 offset:52224
	ds_read_b128 v[180:183], v150 offset:53248
	ds_read_b128 v[196:199], v150 offset:54272
	ds_read_b128 v[200:203], v150 offset:55296
	ds_read_b128 v[204:207], v150 offset:56320
	global_load_lds_dwordx4 v[226:227], off
	v_lshl_add_u64 v[224:225], v[224:225], 0, s[52:53]
	s_mov_b32 m0, s34
	s_nop 0
	global_load_lds_dwordx4 v[224:225], off
	s_add_i32 s4, s4, s21
	v_lshl_add_u64 v[238:239], v[184:185], 0, s[46:47]
	s_mov_b32 m0, s4
	s_nop 0
	global_load_lds_dwordx4 v[238:239], off
	v_lshl_add_u64 v[238:239], v[184:185], 0, s[52:53]
	s_add_i32 m0, s4, 0x2000
	s_nop 0
	global_load_lds_dwordx4 v[238:239], off
	s_add_i32 s4, s5, s21
	v_lshl_add_u64 v[240:241], v[184:185], 0, s[54:55]
	s_mov_b32 m0, s4
	s_nop 0
	global_load_lds_dwordx4 v[240:241], off
	v_lshl_add_u64 v[240:241], v[184:185], 0, s[58:59]
	s_add_i32 m0, s4, 0x2000
	s_nop 0
	global_load_lds_dwordx4 v[240:241], off
	s_waitcnt vmcnt(8)
	s_waitcnt lgkmcnt(0)
	s_barrier
	s_setprio 3
	v_mfma_f32_16x16x32_bf16 v[68:71], v[140:143], v[160:163], v[68:71]
	v_mfma_f32_16x16x32_bf16 v[60:63], v[152:155], v[160:163], v[60:63]
	v_mfma_f32_16x16x32_bf16 v[52:55], v[140:143], v[172:175], v[52:55]
	v_mfma_f32_16x16x32_bf16 v[44:47], v[152:155], v[172:175], v[44:47]
	v_mfma_f32_16x16x32_bf16 v[36:39], v[140:143], v[180:183], v[36:39]
	v_mfma_f32_16x16x32_bf16 v[28:31], v[152:155], v[180:183], v[28:31]
	v_mfma_f32_16x16x32_bf16 v[20:23], v[140:143], v[200:203], v[20:23]
	v_mfma_f32_16x16x32_bf16 v[12:15], v[152:155], v[200:203], v[12:15]
	v_mfma_f32_16x16x32_bf16 v[68:71], v[144:147], v[164:167], v[68:71]
	v_mfma_f32_16x16x32_bf16 v[60:63], v[156:159], v[164:167], v[60:63]
	v_mfma_f32_16x16x32_bf16 v[52:55], v[144:147], v[176:179], v[52:55]
	v_mfma_f32_16x16x32_bf16 v[44:47], v[156:159], v[176:179], v[44:47]
	v_mfma_f32_16x16x32_bf16 v[36:39], v[144:147], v[196:199], v[36:39]
	v_mfma_f32_16x16x32_bf16 v[28:31], v[156:159], v[196:199], v[28:31]
	v_mfma_f32_16x16x32_bf16 v[20:23], v[144:147], v[204:207], v[20:23]
	v_mfma_f32_16x16x32_bf16 v[12:15], v[156:159], v[204:207], v[12:15]
	v_mfma_f32_16x16x32_bf16 v[64:67], v[208:211], v[160:163], v[64:67]
	v_mfma_f32_16x16x32_bf16 v[56:59], v[216:219], v[160:163], v[56:59]
	v_mfma_f32_16x16x32_bf16 v[48:51], v[208:211], v[172:175], v[48:51]
	v_mfma_f32_16x16x32_bf16 v[40:43], v[216:219], v[172:175], v[40:43]
	v_mfma_f32_16x16x32_bf16 v[32:35], v[208:211], v[180:183], v[32:35]
	v_mfma_f32_16x16x32_bf16 v[24:27], v[216:219], v[180:183], v[24:27]
	v_mfma_f32_16x16x32_bf16 v[16:19], v[208:211], v[200:203], v[16:19]
	v_mfma_f32_16x16x32_bf16 v[8:11], v[216:219], v[200:203], v[8:11]
	v_mfma_f32_16x16x32_bf16 v[64:67], v[212:215], v[164:167], v[64:67]
	v_mfma_f32_16x16x32_bf16 v[56:59], v[220:223], v[164:167], v[56:59]
	v_mfma_f32_16x16x32_bf16 v[48:51], v[212:215], v[176:179], v[48:51]
	v_mfma_f32_16x16x32_bf16 v[40:43], v[220:223], v[176:179], v[40:43]
	v_mfma_f32_16x16x32_bf16 v[32:35], v[212:215], v[196:199], v[32:35]
	v_mfma_f32_16x16x32_bf16 v[24:27], v[220:223], v[196:199], v[24:27]
	v_mfma_f32_16x16x32_bf16 v[16:19], v[212:215], v[204:207], v[16:19]
	v_mfma_f32_16x16x32_bf16 v[8:11], v[220:223], v[204:207], v[8:11]
	s_setprio 0
	s_add_i32 s18, s18, 2
	s_add_u32 s2, s2, 0x100
	s_addc_u32 s3, s3, 0
	s_add_u32 s16, s16, 0x100
	s_addc_u32 s17, s17, 0
	s_cmp_gt_u32 s18, 13
	s_barrier
	s_cbranch_scc0 .LBB0_1120
	v_readfirstlane_b32 s2, v148
	s_lshr_b32 s4, s2, 1
	s_and_b32 s4, s4, 0x60
	v_lshrrev_b32_e32 v0, 1, v148
	v_and_or_b32 v0, v0, 24, s4
	v_and_b32_e32 v140, 15, v148
	s_lshl_b32 s4, s38, 10
	s_and_b32 s3, s2, 0xffffff00
	s_add_i32 s4, s4, s3
	v_lshl_add_u32 v141, v140, 2, s4
	v_add_u32_e32 v141, 0x20010, v141
	ds_read_b32 v240, v141
	ds_read_b32 v242, v141 offset:64
	ds_read_b32 v244, v141 offset:128
	ds_read_b32 v246, v141 offset:192
	ds_read_b32 v248, v141 offset:512
	ds_read_b32 v250, v141 offset:576
	ds_read_b32 v252, v141 offset:640
	ds_read_b32 v254, v141 offset:704
	s_ashr_i32 s3, s2, 2
	s_andn2_b32 s3, s3, 63
	v_or_b32_e32 v140, s3, v140
	v_lshl_add_u32 v140, s37, 8, v140
	v_mul_lo_u32 v140, v140, s76
	s_lshl_b32 s3, s33, 8
	v_lshlrev_b32_e32 v0, 1, v0
	v_add3_u32 v140, v140, v0, s3
	s_mov_b64 s[4:5], s[6:7]
	s_mov_b32 s2, 0xbfb8aa3b
	s_mov_b32 s100, 1.0
	s_waitcnt lgkmcnt(0)
; __device__ __forceinline__ float sigmoidf_(float v) { return __builtin_amdgcn_rcpf(1.0f + __expf(-v)); }
; __device__ __forceinline__ u32x4 pack8(const f32x4 a, const f32x4 b) { u32x4 w; w.x = cvt_pk_bf16(a[0], a[1]); w.y = cvt_pk_bf16(a[2], a[3]); w.z = cvt_pk_bf16(b[0], b[1]); w.w = cvt_pk_bf16(b[2], b[3]); return w; }
; #define MEMFENCE asm volatile("" ::: "memory")
;     template <int KIND> __device__ __forceinline__ void run(f32x4 (&acc)[2][2][4][2], const Unit& u, int tid_in) const {
;     ...
;                 for (int m = 0; m < 4; ++m) { int row = rbase + ai * 128 + m * 16; asm volatile("" : "+v"(row)); const float r = rs[ai * 4 + m]; f32x4 o[2];
; #pragma unroll
;                     for (int n = 0; n < 2; ++n) { const f32x4 g = acc[ai][0][m][n] * r, v = acc[ai][1][m][n] * r;
; #pragma unroll
;                         for (int j = 0; j < 4; ++j) o[n][j] = g[j] * sigmoidf_(g[j]) * v[j]; }
;                     *(u32x4*)(act + (size_t)row * ZW + u.pn * 128 + cl) = pack8(o[0], o[1]); MEMFENCE; }
	v_pk_mul_f32 v[132:133], v[132:133], v[240:241] op_sel_hi:[1,0]
	v_pk_mul_f32 v[128:129], v[128:129], v[240:241] op_sel_hi:[1,0]
	v_pk_mul_f32 v[216:217], v[132:133], s[2:3] op_sel_hi:[1,0]
	v_pk_mul_f32 v[134:135], v[134:135], v[240:241] op_sel_hi:[1,0]
	v_pk_mul_f32 v[130:131], v[130:131], v[240:241] op_sel_hi:[1,0]
	v_pk_mul_f32 v[218:219], v[134:135], s[2:3] op_sel_hi:[1,0]
	v_pk_mul_f32 v[124:125], v[124:125], v[240:241] op_sel_hi:[1,0]
	v_pk_mul_f32 v[120:121], v[120:121], v[240:241] op_sel_hi:[1,0]
	v_pk_mul_f32 v[220:221], v[124:125], s[2:3] op_sel_hi:[1,0]
	v_pk_mul_f32 v[126:127], v[126:127], v[240:241] op_sel_hi:[1,0]
	v_pk_mul_f32 v[122:123], v[122:123], v[240:241] op_sel_hi:[1,0]
	v_pk_mul_f32 v[222:223], v[126:127], s[2:3] op_sel_hi:[1,0]
	v_exp_f32_e32 v216, v216
	v_exp_f32_e32 v217, v217
	v_exp_f32_e32 v218, v218
	v_exp_f32_e32 v219, v219
	v_exp_f32_e32 v220, v220
	v_exp_f32_e32 v221, v221
	v_exp_f32_e32 v222, v222
	v_exp_f32_e32 v223, v223
	v_pk_add_f32 v[216:217], v[216:217], s[100:101] op_sel_hi:[1,0]
	v_pk_add_f32 v[218:219], v[218:219], s[100:101] op_sel_hi:[1,0]
	v_pk_add_f32 v[220:221], v[220:221], s[100:101] op_sel_hi:[1,0]
	v_pk_add_f32 v[222:223], v[222:223], s[100:101] op_sel_hi:[1,0]
	v_rcp_f32_e32 v216, v216
	v_rcp_f32_e32 v217, v217
	v_rcp_f32_e32 v218, v218
	v_rcp_f32_e32 v219, v219
	v_rcp_f32_e32 v220, v220
	v_rcp_f32_e32 v221, v221
	v_rcp_f32_e32 v222, v222
	v_rcp_f32_e32 v223, v223
	v_pk_mul_f32 v[132:133], v[132:133], v[216:217]
	v_pk_mul_f32 v[134:135], v[134:135], v[218:219]
	v_pk_mul_f32 v[124:125], v[124:125], v[220:221]
	v_pk_mul_f32 v[126:127], v[126:127], v[222:223]
	v_pk_mul_f32 v[132:133], v[132:133], v[128:129]
	v_pk_mul_f32 v[134:135], v[134:135], v[130:131]
	v_pk_mul_f32 v[124:125], v[124:125], v[120:121]
	v_pk_mul_f32 v[126:127], v[126:127], v[122:123]
	v_cvt_pk_bf16_f32 v236, v132, v133
	v_cvt_pk_bf16_f32 v237, v134, v135
	v_cvt_pk_bf16_f32 v238, v124, v125
	v_cvt_pk_bf16_f32 v239, v126, v127
	global_store_dwordx4 v140, v[236:239], s[4:5]
	s_add_u32 s4, s4, 0x16000
	s_addc_u32 s5, s5, 0
	v_pk_mul_f32 v[116:117], v[116:117], v[242:243] op_sel_hi:[1,0]
	v_pk_mul_f32 v[112:113], v[112:113], v[242:243] op_sel_hi:[1,0]
	v_pk_mul_f32 v[216:217], v[116:117], s[2:3] op_sel_hi:[1,0]
	v_pk_mul_f32 v[118:119], v[118:119], v[242:243] op_sel_hi:[1,0]
	v_pk_mul_f32 v[114:115], v[114:115], v[242:243] op_sel_hi:[1,0]
	v_pk_mul_f32 v[218:219], v[118:119], s[2:3] op_sel_hi:[1,0]
	v_pk_mul_f32 v[108:109], v[108:109], v[242:243] op_sel_hi:[1,0]
	v_pk_mul_f32 v[104:105], v[104:105], v[242:243] op_sel_hi:[1,0]
	v_pk_mul_f32 v[220:221], v[108:109], s[2:3] op_sel_hi:[1,0]
	v_pk_mul_f32 v[110:111], v[110:111], v[242:243] op_sel_hi:[1,0]
	v_pk_mul_f32 v[106:107], v[106:107], v[242:243] op_sel_hi:[1,0]
	v_pk_mul_f32 v[222:223], v[110:111], s[2:3] op_sel_hi:[1,0]
	v_exp_f32_e32 v216, v216
	v_exp_f32_e32 v217, v217
	v_exp_f32_e32 v218, v218
	v_exp_f32_e32 v219, v219
	v_exp_f32_e32 v220, v220
	v_exp_f32_e32 v221, v221
	v_exp_f32_e32 v222, v222
	v_exp_f32_e32 v223, v223
	v_pk_add_f32 v[216:217], v[216:217], s[100:101] op_sel_hi:[1,0]
	v_pk_add_f32 v[218:219], v[218:219], s[100:101] op_sel_hi:[1,0]
	v_pk_add_f32 v[220:221], v[220:221], s[100:101] op_sel_hi:[1,0]
	v_pk_add_f32 v[222:223], v[222:223], s[100:101] op_sel_hi:[1,0]
	v_rcp_f32_e32 v216, v216
	v_rcp_f32_e32 v217, v217
	v_rcp_f32_e32 v218, v218
	v_rcp_f32_e32 v219, v219
	v_rcp_f32_e32 v220, v220
	v_rcp_f32_e32 v221, v221
	v_rcp_f32_e32 v222, v222
	v_rcp_f32_e32 v223, v223
	v_pk_mul_f32 v[116:117], v[116:117], v[216:217]
	v_pk_mul_f32 v[118:119], v[118:119], v[218:219]
	v_pk_mul_f32 v[108:109], v[108:109], v[220:221]
	v_pk_mul_f32 v[110:111], v[110:111], v[222:223]
	v_pk_mul_f32 v[116:117], v[116:117], v[112:113]
	v_pk_mul_f32 v[118:119], v[118:119], v[114:115]
	v_pk_mul_f32 v[108:109], v[108:109], v[104:105]
	v_pk_mul_f32 v[110:111], v[110:111], v[106:107]
	v_cvt_pk_bf16_f32 v236, v116, v117
	v_cvt_pk_bf16_f32 v237, v118, v119
	v_cvt_pk_bf16_f32 v238, v108, v109
	v_cvt_pk_bf16_f32 v239, v110, v111
	global_store_dwordx4 v140, v[236:239], s[4:5]
	s_add_u32 s4, s4, 0x16000
	s_addc_u32 s5, s5, 0
	v_pk_mul_f32 v[100:101], v[100:101], v[244:245] op_sel_hi:[1,0]
	v_pk_mul_f32 v[96:97], v[96:97], v[244:245] op_sel_hi:[1,0]
	v_pk_mul_f32 v[216:217], v[100:101], s[2:3] op_sel_hi:[1,0]
	v_pk_mul_f32 v[102:103], v[102:103], v[244:245] op_sel_hi:[1,0]
	v_pk_mul_f32 v[98:99], v[98:99], v[244:245] op_sel_hi:[1,0]
	v_pk_mul_f32 v[218:219], v[102:103], s[2:3] op_sel_hi:[1,0]
	v_pk_mul_f32 v[92:93], v[92:93], v[244:245] op_sel_hi:[1,0]
	v_pk_mul_f32 v[88:89], v[88:89], v[244:245] op_sel_hi:[1,0]
	v_pk_mul_f32 v[220:221], v[92:93], s[2:3] op_sel_hi:[1,0]
	v_pk_mul_f32 v[94:95], v[94:95], v[244:245] op_sel_hi:[1,0]
	v_pk_mul_f32 v[90:91], v[90:91], v[244:245] op_sel_hi:[1,0]
	v_pk_mul_f32 v[222:223], v[94:95], s[2:3] op_sel_hi:[1,0]
	v_exp_f32_e32 v216, v216
	v_exp_f32_e32 v217, v217
	v_exp_f32_e32 v218, v218
	v_exp_f32_e32 v219, v219
	v_exp_f32_e32 v220, v220
	v_exp_f32_e32 v221, v221
	v_exp_f32_e32 v222, v222
	v_exp_f32_e32 v223, v223
	v_pk_add_f32 v[216:217], v[216:217], s[100:101] op_sel_hi:[1,0]
	v_pk_add_f32 v[218:219], v[218:219], s[100:101] op_sel_hi:[1,0]
	v_pk_add_f32 v[220:221], v[220:221], s[100:101] op_sel_hi:[1,0]
	v_pk_add_f32 v[222:223], v[222:223], s[100:101] op_sel_hi:[1,0]
	v_rcp_f32_e32 v216, v216
	v_rcp_f32_e32 v217, v217
	v_rcp_f32_e32 v218, v218
	v_rcp_f32_e32 v219, v219
	v_rcp_f32_e32 v220, v220
	v_rcp_f32_e32 v221, v221
	v_rcp_f32_e32 v222, v222
	v_rcp_f32_e32 v223, v223
	v_pk_mul_f32 v[100:101], v[100:101], v[216:217]
	v_pk_mul_f32 v[102:103], v[102:103], v[218:219]
; __device__ __forceinline__ float sigmoidf_(float v) { return __builtin_amdgcn_rcpf(1.0f + __expf(-v)); }
; __device__ __forceinline__ u32x4 pack8(const f32x4 a, const f32x4 b) { u32x4 w; w.x = cvt_pk_bf16(a[0], a[1]); w.y = cvt_pk_bf16(a[2], a[3]); w.z = cvt_pk_bf16(b[0], b[1]); w.w = cvt_pk_bf16(b[2], b[3]); return w; }
; #define MEMFENCE asm volatile("" ::: "memory")
;     template <int KIND> __device__ __forceinline__ void run(f32x4 (&acc)[2][2][4][2], const Unit& u, int tid_in) const {
;     ...
;                 for (int m = 0; m < 4; ++m) { int row = rbase + ai * 128 + m * 16; asm volatile("" : "+v"(row)); const float r = rs[ai * 4 + m]; f32x4 o[2];
; #pragma unroll
;                     for (int n = 0; n < 2; ++n) { const f32x4 g = acc[ai][0][m][n] * r, v = acc[ai][1][m][n] * r;
; #pragma unroll
;                         for (int j = 0; j < 4; ++j) o[n][j] = g[j] * sigmoidf_(g[j]) * v[j]; }
;                     *(u32x4*)(act + (size_t)row * ZW + u.pn * 128 + cl) = pack8(o[0], o[1]); MEMFENCE; }
	v_pk_mul_f32 v[92:93], v[92:93], v[220:221]
	v_pk_mul_f32 v[94:95], v[94:95], v[222:223]
	v_pk_mul_f32 v[100:101], v[100:101], v[96:97]
	v_pk_mul_f32 v[102:103], v[102:103], v[98:99]
	v_pk_mul_f32 v[92:93], v[92:93], v[88:89]
	v_pk_mul_f32 v[94:95], v[94:95], v[90:91]
	v_cvt_pk_bf16_f32 v236, v100, v101
	v_cvt_pk_bf16_f32 v237, v102, v103
	v_cvt_pk_bf16_f32 v238, v92, v93
	v_cvt_pk_bf16_f32 v239, v94, v95
	global_store_dwordx4 v140, v[236:239], s[4:5]
	s_add_u32 s4, s4, 0x16000
	s_addc_u32 s5, s5, 0
	v_pk_mul_f32 v[84:85], v[84:85], v[246:247] op_sel_hi:[1,0]
	v_pk_mul_f32 v[80:81], v[80:81], v[246:247] op_sel_hi:[1,0]
	v_pk_mul_f32 v[216:217], v[84:85], s[2:3] op_sel_hi:[1,0]
	v_pk_mul_f32 v[86:87], v[86:87], v[246:247] op_sel_hi:[1,0]
	v_pk_mul_f32 v[82:83], v[82:83], v[246:247] op_sel_hi:[1,0]
	v_pk_mul_f32 v[218:219], v[86:87], s[2:3] op_sel_hi:[1,0]
	v_pk_mul_f32 v[76:77], v[76:77], v[246:247] op_sel_hi:[1,0]
	v_pk_mul_f32 v[72:73], v[72:73], v[246:247] op_sel_hi:[1,0]
	v_pk_mul_f32 v[220:221], v[76:77], s[2:3] op_sel_hi:[1,0]
	v_pk_mul_f32 v[78:79], v[78:79], v[246:247] op_sel_hi:[1,0]
	v_pk_mul_f32 v[74:75], v[74:75], v[246:247] op_sel_hi:[1,0]
	v_pk_mul_f32 v[222:223], v[78:79], s[2:3] op_sel_hi:[1,0]
	v_exp_f32_e32 v216, v216
	v_exp_f32_e32 v217, v217
	v_exp_f32_e32 v218, v218
	v_exp_f32_e32 v219, v219
	v_exp_f32_e32 v220, v220
	v_exp_f32_e32 v221, v221
	v_exp_f32_e32 v222, v222
	v_exp_f32_e32 v223, v223
	v_pk_add_f32 v[216:217], v[216:217], s[100:101] op_sel_hi:[1,0]
	v_pk_add_f32 v[218:219], v[218:219], s[100:101] op_sel_hi:[1,0]
	v_pk_add_f32 v[220:221], v[220:221], s[100:101] op_sel_hi:[1,0]
	v_pk_add_f32 v[222:223], v[222:223], s[100:101] op_sel_hi:[1,0]
	v_rcp_f32_e32 v216, v216
	v_rcp_f32_e32 v217, v217
	v_rcp_f32_e32 v218, v218
	v_rcp_f32_e32 v219, v219
	v_rcp_f32_e32 v220, v220
	v_rcp_f32_e32 v221, v221
	v_rcp_f32_e32 v222, v222
	v_rcp_f32_e32 v223, v223
	v_pk_mul_f32 v[84:85], v[84:85], v[216:217]
	v_pk_mul_f32 v[86:87], v[86:87], v[218:219]
	v_pk_mul_f32 v[76:77], v[76:77], v[220:221]
	v_pk_mul_f32 v[78:79], v[78:79], v[222:223]
	v_pk_mul_f32 v[84:85], v[84:85], v[80:81]
	v_pk_mul_f32 v[86:87], v[86:87], v[82:83]
	v_pk_mul_f32 v[76:77], v[76:77], v[72:73]
	v_pk_mul_f32 v[78:79], v[78:79], v[74:75]
	v_cvt_pk_bf16_f32 v236, v84, v85
	v_cvt_pk_bf16_f32 v237, v86, v87
	v_cvt_pk_bf16_f32 v238, v76, v77
	v_cvt_pk_bf16_f32 v239, v78, v79
	global_store_dwordx4 v140, v[236:239], s[4:5]
	s_add_u32 s4, s4, 0x6e000
	s_addc_u32 s5, s5, 0
	v_pk_mul_f32 v[68:69], v[68:69], v[248:249] op_sel_hi:[1,0]
	v_pk_mul_f32 v[64:65], v[64:65], v[248:249] op_sel_hi:[1,0]
	v_pk_mul_f32 v[216:217], v[68:69], s[2:3] op_sel_hi:[1,0]
	v_pk_mul_f32 v[70:71], v[70:71], v[248:249] op_sel_hi:[1,0]
	v_pk_mul_f32 v[66:67], v[66:67], v[248:249] op_sel_hi:[1,0]
	v_pk_mul_f32 v[218:219], v[70:71], s[2:3] op_sel_hi:[1,0]
	v_pk_mul_f32 v[60:61], v[60:61], v[248:249] op_sel_hi:[1,0]
	v_pk_mul_f32 v[56:57], v[56:57], v[248:249] op_sel_hi:[1,0]
	v_pk_mul_f32 v[220:221], v[60:61], s[2:3] op_sel_hi:[1,0]
	v_pk_mul_f32 v[62:63], v[62:63], v[248:249] op_sel_hi:[1,0]
	v_pk_mul_f32 v[58:59], v[58:59], v[248:249] op_sel_hi:[1,0]
	v_pk_mul_f32 v[222:223], v[62:63], s[2:3] op_sel_hi:[1,0]
	v_exp_f32_e32 v216, v216
	v_exp_f32_e32 v217, v217
	v_exp_f32_e32 v218, v218
	v_exp_f32_e32 v219, v219
	v_exp_f32_e32 v220, v220
	v_exp_f32_e32 v221, v221
	v_exp_f32_e32 v222, v222
	v_exp_f32_e32 v223, v223
	v_pk_add_f32 v[216:217], v[216:217], s[100:101] op_sel_hi:[1,0]
	v_pk_add_f32 v[218:219], v[218:219], s[100:101] op_sel_hi:[1,0]
	v_pk_add_f32 v[220:221], v[220:221], s[100:101] op_sel_hi:[1,0]
	v_pk_add_f32 v[222:223], v[222:223], s[100:101] op_sel_hi:[1,0]
	v_rcp_f32_e32 v216, v216
	v_rcp_f32_e32 v217, v217
	v_rcp_f32_e32 v218, v218
	v_rcp_f32_e32 v219, v219
	v_rcp_f32_e32 v220, v220
	v_rcp_f32_e32 v221, v221
	v_rcp_f32_e32 v222, v222
	v_rcp_f32_e32 v223, v223
	v_pk_mul_f32 v[68:69], v[68:69], v[216:217]
	v_pk_mul_f32 v[70:71], v[70:71], v[218:219]
	v_pk_mul_f32 v[60:61], v[60:61], v[220:221]
	v_pk_mul_f32 v[62:63], v[62:63], v[222:223]
	v_pk_mul_f32 v[68:69], v[68:69], v[64:65]
	v_pk_mul_f32 v[70:71], v[70:71], v[66:67]
	v_pk_mul_f32 v[60:61], v[60:61], v[56:57]
	v_pk_mul_f32 v[62:63], v[62:63], v[58:59]
	v_cvt_pk_bf16_f32 v236, v68, v69
	v_cvt_pk_bf16_f32 v237, v70, v71
	v_cvt_pk_bf16_f32 v238, v60, v61
	v_cvt_pk_bf16_f32 v239, v62, v63
	global_store_dwordx4 v140, v[236:239], s[4:5]
	s_add_u32 s4, s4, 0x16000
	s_addc_u32 s5, s5, 0
	v_pk_mul_f32 v[52:53], v[52:53], v[250:251] op_sel_hi:[1,0]
	v_pk_mul_f32 v[48:49], v[48:49], v[250:251] op_sel_hi:[1,0]
	v_pk_mul_f32 v[216:217], v[52:53], s[2:3] op_sel_hi:[1,0]
	v_pk_mul_f32 v[54:55], v[54:55], v[250:251] op_sel_hi:[1,0]
	v_pk_mul_f32 v[50:51], v[50:51], v[250:251] op_sel_hi:[1,0]
	v_pk_mul_f32 v[218:219], v[54:55], s[2:3] op_sel_hi:[1,0]
	v_pk_mul_f32 v[44:45], v[44:45], v[250:251] op_sel_hi:[1,0]
	v_pk_mul_f32 v[40:41], v[40:41], v[250:251] op_sel_hi:[1,0]
	v_pk_mul_f32 v[220:221], v[44:45], s[2:3] op_sel_hi:[1,0]
	v_pk_mul_f32 v[46:47], v[46:47], v[250:251] op_sel_hi:[1,0]
	v_pk_mul_f32 v[42:43], v[42:43], v[250:251] op_sel_hi:[1,0]
	v_pk_mul_f32 v[222:223], v[46:47], s[2:3] op_sel_hi:[1,0]
	v_exp_f32_e32 v216, v216
	v_exp_f32_e32 v217, v217
	v_exp_f32_e32 v218, v218
	v_exp_f32_e32 v219, v219
; __device__ __forceinline__ float sigmoidf_(float v) { return __builtin_amdgcn_rcpf(1.0f + __expf(-v)); }
; __device__ __forceinline__ u32x4 pack8(const f32x4 a, const f32x4 b) { u32x4 w; w.x = cvt_pk_bf16(a[0], a[1]); w.y = cvt_pk_bf16(a[2], a[3]); w.z = cvt_pk_bf16(b[0], b[1]); w.w = cvt_pk_bf16(b[2], b[3]); return w; }
; #define MEMFENCE asm volatile("" ::: "memory")
; #define G_WAIT_V(n) asm volatile("s_waitcnt vmcnt(" #n ")" ::: "memory")
; #define G_BAR __builtin_amdgcn_s_barrier()
;     template <int KIND> __device__ __forceinline__ void run(f32x4 (&acc)[2][2][4][2], const Unit& u, int tid_in) const {
;     ...
;                 for (int m = 0; m < 4; ++m) { int row = rbase + ai * 128 + m * 16; asm volatile("" : "+v"(row)); const float r = rs[ai * 4 + m]; f32x4 o[2];
; #pragma unroll
;                     for (int n = 0; n < 2; ++n) { const f32x4 g = acc[ai][0][m][n] * r, v = acc[ai][1][m][n] * r;
; #pragma unroll
;                         for (int j = 0; j < 4; ++j) o[n][j] = g[j] * sigmoidf_(g[j]) * v[j]; }
;                     *(u32x4*)(act + (size_t)row * ZW + u.pn * 128 + cl) = pack8(o[0], o[1]); MEMFENCE; }
;     ...
;         cur = nxt; cA = nA; cB = nB; ++ui;
;     }
;     G_WAIT_V(0);
;     if (wr == 0) G_BAR;
	v_exp_f32_e32 v220, v220
	v_exp_f32_e32 v221, v221
	v_exp_f32_e32 v222, v222
	v_exp_f32_e32 v223, v223
	v_pk_add_f32 v[216:217], v[216:217], s[100:101] op_sel_hi:[1,0]
	v_pk_add_f32 v[218:219], v[218:219], s[100:101] op_sel_hi:[1,0]
	v_pk_add_f32 v[220:221], v[220:221], s[100:101] op_sel_hi:[1,0]
	v_pk_add_f32 v[222:223], v[222:223], s[100:101] op_sel_hi:[1,0]
	v_rcp_f32_e32 v216, v216
	v_rcp_f32_e32 v217, v217
	v_rcp_f32_e32 v218, v218
	v_rcp_f32_e32 v219, v219
	v_rcp_f32_e32 v220, v220
	v_rcp_f32_e32 v221, v221
	v_rcp_f32_e32 v222, v222
	v_rcp_f32_e32 v223, v223
	v_pk_mul_f32 v[52:53], v[52:53], v[216:217]
	v_pk_mul_f32 v[54:55], v[54:55], v[218:219]
	v_pk_mul_f32 v[44:45], v[44:45], v[220:221]
	v_pk_mul_f32 v[46:47], v[46:47], v[222:223]
	v_pk_mul_f32 v[52:53], v[52:53], v[48:49]
	v_pk_mul_f32 v[54:55], v[54:55], v[50:51]
	v_pk_mul_f32 v[44:45], v[44:45], v[40:41]
	v_pk_mul_f32 v[46:47], v[46:47], v[42:43]
	v_cvt_pk_bf16_f32 v236, v52, v53
	v_cvt_pk_bf16_f32 v237, v54, v55
	v_cvt_pk_bf16_f32 v238, v44, v45
	v_cvt_pk_bf16_f32 v239, v46, v47
	global_store_dwordx4 v140, v[236:239], s[4:5]
	s_add_u32 s4, s4, 0x16000
	s_addc_u32 s5, s5, 0
	v_pk_mul_f32 v[36:37], v[36:37], v[252:253] op_sel_hi:[1,0]
	v_pk_mul_f32 v[32:33], v[32:33], v[252:253] op_sel_hi:[1,0]
	v_pk_mul_f32 v[216:217], v[36:37], s[2:3] op_sel_hi:[1,0]
	v_pk_mul_f32 v[38:39], v[38:39], v[252:253] op_sel_hi:[1,0]
	v_pk_mul_f32 v[34:35], v[34:35], v[252:253] op_sel_hi:[1,0]
	v_pk_mul_f32 v[218:219], v[38:39], s[2:3] op_sel_hi:[1,0]
	v_pk_mul_f32 v[28:29], v[28:29], v[252:253] op_sel_hi:[1,0]
	v_pk_mul_f32 v[24:25], v[24:25], v[252:253] op_sel_hi:[1,0]
	v_pk_mul_f32 v[220:221], v[28:29], s[2:3] op_sel_hi:[1,0]
	v_pk_mul_f32 v[30:31], v[30:31], v[252:253] op_sel_hi:[1,0]
	v_pk_mul_f32 v[26:27], v[26:27], v[252:253] op_sel_hi:[1,0]
	v_pk_mul_f32 v[222:223], v[30:31], s[2:3] op_sel_hi:[1,0]
	v_exp_f32_e32 v216, v216
	v_exp_f32_e32 v217, v217
	v_exp_f32_e32 v218, v218
	v_exp_f32_e32 v219, v219
	v_exp_f32_e32 v220, v220
	v_exp_f32_e32 v221, v221
	v_exp_f32_e32 v222, v222
	v_exp_f32_e32 v223, v223
	v_pk_add_f32 v[216:217], v[216:217], s[100:101] op_sel_hi:[1,0]
	v_pk_add_f32 v[218:219], v[218:219], s[100:101] op_sel_hi:[1,0]
	v_pk_add_f32 v[220:221], v[220:221], s[100:101] op_sel_hi:[1,0]
	v_pk_add_f32 v[222:223], v[222:223], s[100:101] op_sel_hi:[1,0]
	v_rcp_f32_e32 v216, v216
	v_rcp_f32_e32 v217, v217
	v_rcp_f32_e32 v218, v218
	v_rcp_f32_e32 v219, v219
	v_rcp_f32_e32 v220, v220
	v_rcp_f32_e32 v221, v221
	v_rcp_f32_e32 v222, v222
	v_rcp_f32_e32 v223, v223
	v_pk_mul_f32 v[36:37], v[36:37], v[216:217]
	v_pk_mul_f32 v[38:39], v[38:39], v[218:219]
	v_pk_mul_f32 v[28:29], v[28:29], v[220:221]
	v_pk_mul_f32 v[30:31], v[30:31], v[222:223]
	v_pk_mul_f32 v[36:37], v[36:37], v[32:33]
	v_pk_mul_f32 v[38:39], v[38:39], v[34:35]
	v_pk_mul_f32 v[28:29], v[28:29], v[24:25]
	v_pk_mul_f32 v[30:31], v[30:31], v[26:27]
	v_cvt_pk_bf16_f32 v236, v36, v37
	v_cvt_pk_bf16_f32 v237, v38, v39
	v_cvt_pk_bf16_f32 v238, v28, v29
	v_cvt_pk_bf16_f32 v239, v30, v31
	global_store_dwordx4 v140, v[236:239], s[4:5]
	s_add_u32 s4, s4, 0x16000
	s_addc_u32 s5, s5, 0
	v_pk_mul_f32 v[20:21], v[20:21], v[254:255] op_sel_hi:[1,0]
	v_pk_mul_f32 v[16:17], v[16:17], v[254:255] op_sel_hi:[1,0]
	v_pk_mul_f32 v[216:217], v[20:21], s[2:3] op_sel_hi:[1,0]
	v_pk_mul_f32 v[22:23], v[22:23], v[254:255] op_sel_hi:[1,0]
	v_pk_mul_f32 v[18:19], v[18:19], v[254:255] op_sel_hi:[1,0]
	v_pk_mul_f32 v[218:219], v[22:23], s[2:3] op_sel_hi:[1,0]
	v_pk_mul_f32 v[12:13], v[12:13], v[254:255] op_sel_hi:[1,0]
	v_pk_mul_f32 v[8:9], v[8:9], v[254:255] op_sel_hi:[1,0]
	v_pk_mul_f32 v[220:221], v[12:13], s[2:3] op_sel_hi:[1,0]
	v_pk_mul_f32 v[14:15], v[14:15], v[254:255] op_sel_hi:[1,0]
	v_pk_mul_f32 v[10:11], v[10:11], v[254:255] op_sel_hi:[1,0]
	v_pk_mul_f32 v[222:223], v[14:15], s[2:3] op_sel_hi:[1,0]
	v_exp_f32_e32 v216, v216
	v_exp_f32_e32 v217, v217
	v_exp_f32_e32 v218, v218
	v_exp_f32_e32 v219, v219
	v_exp_f32_e32 v220, v220
	v_exp_f32_e32 v221, v221
	v_exp_f32_e32 v222, v222
	v_exp_f32_e32 v223, v223
	v_pk_add_f32 v[216:217], v[216:217], s[100:101] op_sel_hi:[1,0]
	v_pk_add_f32 v[218:219], v[218:219], s[100:101] op_sel_hi:[1,0]
	v_pk_add_f32 v[220:221], v[220:221], s[100:101] op_sel_hi:[1,0]
	v_pk_add_f32 v[222:223], v[222:223], s[100:101] op_sel_hi:[1,0]
	v_rcp_f32_e32 v216, v216
	v_rcp_f32_e32 v217, v217
	v_rcp_f32_e32 v218, v218
	v_rcp_f32_e32 v219, v219
	v_rcp_f32_e32 v220, v220
	v_rcp_f32_e32 v221, v221
	v_rcp_f32_e32 v222, v222
	v_rcp_f32_e32 v223, v223
	v_pk_mul_f32 v[20:21], v[20:21], v[216:217]
	v_pk_mul_f32 v[22:23], v[22:23], v[218:219]
	v_pk_mul_f32 v[12:13], v[12:13], v[220:221]
	v_pk_mul_f32 v[14:15], v[14:15], v[222:223]
	v_pk_mul_f32 v[20:21], v[20:21], v[16:17]
	v_pk_mul_f32 v[22:23], v[22:23], v[18:19]
	v_pk_mul_f32 v[12:13], v[12:13], v[8:9]
	v_pk_mul_f32 v[14:15], v[14:15], v[10:11]
	v_cvt_pk_bf16_f32 v236, v20, v21
	v_cvt_pk_bf16_f32 v237, v22, v23
	v_cvt_pk_bf16_f32 v238, v12, v13
	v_cvt_pk_bf16_f32 v239, v14, v15
	global_store_dwordx4 v140, v[236:239], s[4:5]
	s_mov_b32 s38, s11
	s_mov_b32 s37, s10
	s_mov_b64 s[18:19], s[14:15]
	s_mov_b64 s[16:17], s[12:13]
	s_mov_b32 s33, s36
	s_and_b64 vcc, exec, s[8:9]
	s_cbranch_vccz .LBB0_1115
	s_waitcnt vmcnt(0)
	s_cmpk_gt_u32 s20, 0xff
	s_cbranch_scc1 .LBB0_1124
	s_barrier
